# warm_twiddle_table_before_L2_phase
# speedup vs baseline: 1.0005x; 1.0005x over previous
.LBB0_337:
	v_readlane_b32 s94, v254, 5
	s_cmp_lt_u32 s94, 64
	s_cbranch_scc1 .Lwarm_skip
	v_readlane_b32 s90, v254, 0
	v_readlane_b32 s91, v254, 1
	s_load_dwordx2 s[92:93], s[90:91], 0xc0
	s_add_i32 s94, s94, 0xffffffc0
	s_mul_i32 s94, s94, 0x6000
	v_lshlrev_b32_e32 v250, 4, v0
	s_waitcnt lgkmcnt(0)
	s_add_u32 s92, s92, 0x1ea40000
	s_addc_u32 s93, s93, 0
	s_add_u32 s92, s92, s94
	s_addc_u32 s93, s93, 0
	global_load_dwordx4 v[234:237], v250, s[92:93]
	s_add_u32 s92, s92, 0x2000
	s_addc_u32 s93, s93, 0
	global_load_dwordx4 v[238:241], v250, s[92:93]
	s_add_u32 s92, s92, 0x2000
	s_addc_u32 s93, s93, 0
	global_load_dwordx4 v[242:245], v250, s[92:93]
